# code placement: FoX steady-loop head at 0 mod 8 (was 4 mod 8), otherwise identical to the stacked variant
# baseline (speedup 1.0000x reference)
.LBB0_288:
	ds_read2_b32 v[246:247], v171 offset1:32
	s_waitcnt lgkmcnt(0)
	s_nop 0
